# P0 rmsnorm pass: the four gain-vector loads (and their vmcnt(0) round trips) hoisted out of the row loop into registers
# speedup vs baseline: 1.0221x; 1.0020x over previous
; __device__ __forceinline__ void rms_pass(const float* X, const float* g, bf16_t* O, float* F, int rows, int gw, int NGW) {
;     int tid_ = threadIdx.x; asm volatile("" : "+v"(tid_)); const int lane = tid_ & 63;
;     const f32x4* gr = (const f32x4*)g + lane;
;     for (int m = gw; m < rows; m += 2 * NGW) {
;         const bool two = (m + NGW) < rows; const int m1 = two ? m + NGW : m;
;         const f32x4* x0 = (const f32x4*)(X + (size_t)m * 1024) + lane; const f32x4* x1 = (const f32x4*)(X + (size_t)m1 * 1024) + lane;
;         f32x4 v0[4], v1[4]; float s0 = 0.f, s1 = 0.f;
; #pragma unroll
;         for (int j = 0; j < 4; ++j) { v0[j] = x0[64 * j]; v1[j] = x1[64 * j]; }
.LBB0_1320:
	v_writelane_b32 v253, s30, 8
	s_nop 1
	v_writelane_b32 v253, s31, 9
	s_or_b64 exec, exec, s[4:5]
	s_add_u32 s94, s86, 0x14100000
	s_load_dwordx2 s[4:5], s[82:83], 0x0
	s_addc_u32 s95, s87, 0
	s_cmp_lt_i32 s78, 0x10000
	s_cselect_b64 s[6:7], -1, 0
	v_mov_b32_e32 v2, v198
	v_writelane_b32 v253, s6, 6
	s_cmp_gt_i32 s78, 0xffff
	v_mbcnt_lo_u32_b32 v199, -1, 0
	v_writelane_b32 v253, s7, 7
	s_cbranch_scc1 .LBB0_1331
	s_load_dwordx2 s[6:7], s[82:83], 0x10
	v_and_b32_e32 v4, 63, v2
	v_mov_b32_e32 v3, 0
	v_lshlrev_b32_e32 v2, 4, v4
	s_waitcnt lgkmcnt(0)
	v_lshl_add_u64 v[36:37], s[4:5], 0, v[2:3]
	v_lshl_add_u64 v[38:39], s[6:7], 0, v[2:3]
	v_lshlrev_b32_e32 v2, 3, v4
	v_lshl_add_u64 v[40:41], s[94:95], 0, v[2:3]
	v_mbcnt_hi_u32_b32 v2, -1, v199
	v_and_b32_e32 v3, 64, v2
	v_add_u32_e32 v3, 64, v3
	v_xor_b32_e32 v4, 1, v2
	v_cmp_lt_i32_e32 vcc, v4, v3
	v_mov_b32_e32 v55, 0x358637bd
	s_mov_b32 s13, 0xf800000
	v_cndmask_b32_e32 v4, v2, v4, vcc
	v_lshlrev_b32_e32 v35, 2, v4
	v_xor_b32_e32 v4, 2, v2
	v_cmp_lt_i32_e32 vcc, v4, v3
	v_mov_b32_e32 v56, 0x260
	s_mov_b32 s6, s78
	v_cndmask_b32_e32 v4, v2, v4, vcc
	v_lshlrev_b32_e32 v50, 2, v4
	v_xor_b32_e32 v4, 4, v2
	v_cmp_lt_i32_e32 vcc, v4, v3
	s_nop 1
	v_cndmask_b32_e32 v4, v2, v4, vcc
	v_lshlrev_b32_e32 v51, 2, v4
	v_xor_b32_e32 v4, 8, v2
	v_cmp_lt_i32_e32 vcc, v4, v3
	s_nop 1
	v_cndmask_b32_e32 v4, v2, v4, vcc
	v_lshlrev_b32_e32 v52, 2, v4
	v_xor_b32_e32 v4, 16, v2
	v_cmp_lt_i32_e32 vcc, v4, v3
	s_nop 1
	v_cndmask_b32_e32 v4, v2, v4, vcc
	v_lshlrev_b32_e32 v53, 2, v4
	v_xor_b32_e32 v4, 32, v2
	v_cmp_lt_i32_e32 vcc, v4, v3
	s_nop 1
	v_cndmask_b32_e32 v2, v2, v4, vcc
	v_lshlrev_b32_e32 v54, 2, v2
	global_load_dwordx4 v[208:211], v[38:39], off
	global_load_dwordx4 v[212:215], v[38:39], off offset:1024
	global_load_dwordx4 v[216:219], v[38:39], off offset:2048
	global_load_dwordx4 v[220:223], v[38:39], off offset:3072
	s_branch .LBB0_1323

; __device__ __forceinline__ unsigned cvt_pk_bf16(float lo, float hi) { unsigned r; asm volatile("v_cvt_pk_bf16_f32 %0, %1, %2" : "=v"(r) : "v"(lo), "v"(hi)); return r; }
; __device__ __forceinline__ void rms_pass(const float* X, const float* g, bf16_t* O, float* F, int rows, int gw, int NGW) {
;     ...
;     for (int m = gw; m < rows; m += 2 * NGW) {
;         const bool two = (m + NGW) < rows; const int m1 = two ? m + NGW : m;
;         const f32x4* x0 = (const f32x4*)(X + (size_t)m * 1024) + lane; const f32x4* x1 = (const f32x4*)(X + (size_t)m1 * 1024) + lane;
;         f32x4 v0[4], v1[4]; float s0 = 0.f, s1 = 0.f;
; #pragma unroll
;         for (int j = 0; j < 4; ++j) { v0[j] = x0[64 * j]; v1[j] = x1[64 * j]; }
; #pragma unroll
;         for (int j = 0; j < 4; ++j) { s0 += (v0[j].x * v0[j].x + v0[j].y * v0[j].y) + (v0[j].z * v0[j].z + v0[j].w * v0[j].w); s1 += (v1[j].x * v1[j].x + v1[j].y * v1[j].y) + (v1[j].z * v1[j].z + v1[j].w * v1[j].w); }
;         const float r0 = 1.0f / sqrtf(wave_sum(s0) * (1.f / 1024.f) + 1e-6f), r1 = 1.0f / sqrtf(wave_sum(s1) * (1.f / 1024.f) + 1e-6f);
; #pragma unroll
;         for (int j = 0; j < 4; ++j) {
;             const f32x4 gg = gr[64 * j]; const f32x4 y0 = v0[j] * r0 * gg, y1 = v1[j] * r1 * gg;
;             u32x2 w0, w1; w0.x = cvt_pk_bf16(y0.x, y0.y); w0.y = cvt_pk_bf16(y0.z, y0.w); w1.x = cvt_pk_bf16(y1.x, y1.y); w1.y = cvt_pk_bf16(y1.z, y1.w);
;             *((u32x2*)(O + (size_t)m * 1024) + lane + 64 * j) = w0;
.LBB0_1323:
	s_add_i32 s26, s6, s77
	s_cmp_lt_i32 s26, 0x10000
	s_cselect_b64 s[14:15], -1, 0
	s_and_b64 s[8:9], s[14:15], exec
	s_cselect_b32 s8, s26, s6
	s_ashr_i32 s7, s6, 31
	s_lshl_b64 s[30:31], s[6:7], 12
	v_lshl_add_u64 v[6:7], v[36:37], 0, s[30:31]
	s_ashr_i32 s9, s8, 31
	global_load_dwordx4 v[26:29], v[6:7], off
	global_load_dwordx4 v[18:21], v[6:7], off offset:1024
	global_load_dwordx4 v[2:5], v[6:7], off offset:3072
	global_load_dwordx4 v[14:17], v[6:7], off offset:2048
	s_lshl_b64 s[30:31], s[8:9], 12
	v_lshl_add_u64 v[10:11], v[36:37], 0, s[30:31]
	global_load_dwordx4 v[30:33], v[10:11], off
	global_load_dwordx4 v[22:25], v[10:11], off offset:1024
	global_load_dwordx4 v[6:9], v[10:11], off offset:3072
	s_nop 0
	global_load_dwordx4 v[10:13], v[10:11], off offset:2048
	s_lshl_b64 s[30:31], s[6:7], 11
	s_lshl_b64 s[34:35], s[8:9], 11
	s_cmp_gt_i32 s26, 0xffff
	s_waitcnt vmcnt(7)
	v_pk_mul_f32 v[42:43], v[28:29], v[28:29]
	v_pk_mul_f32 v[44:45], v[26:27], v[26:27]
	s_waitcnt vmcnt(6)
	v_pk_mul_f32 v[46:47], v[20:21], v[20:21]
	v_pk_mul_f32 v[48:49], v[18:19], v[18:19]
	s_waitcnt vmcnt(4)
	v_mul_f32_e32 v58, v15, v15
	v_mul_f32_e32 v60, v17, v17
	v_pk_mov_b32 v[62:63], v[44:45], v[42:43] op_sel:[1,0]
	v_mov_b32_e32 v45, v43
	s_waitcnt vmcnt(3)
	v_pk_mul_f32 v[42:43], v[32:33], v[32:33]
	v_pk_mul_f32 v[64:65], v[30:31], v[30:31]
	v_pk_mov_b32 v[66:67], v[48:49], v[46:47] op_sel:[1,0]
	v_mov_b32_e32 v49, v47
	s_waitcnt vmcnt(2)
	v_pk_mul_f32 v[46:47], v[24:25], v[24:25]
	v_pk_mul_f32 v[68:69], v[22:23], v[22:23]
	v_mul_f32_e32 v57, v4, v4
	v_mul_f32_e32 v71, v5, v5
	v_pk_fma_f32 v[58:59], v[14:15], v[14:15], v[58:59] op_sel_hi:[1,1,0]
	v_pk_fma_f32 v[60:61], v[16:17], v[16:17], v[60:61] op_sel_hi:[1,1,0]
	v_pk_add_f32 v[44:45], v[62:63], v[44:45]
	v_pk_mov_b32 v[62:63], v[64:65], v[42:43] op_sel:[1,0]
	v_mov_b32_e32 v65, v43
	v_pk_add_f32 v[42:43], v[66:67], v[48:49]
	v_pk_mov_b32 v[48:49], v[68:69], v[46:47] op_sel:[1,0]
	v_mov_b32_e32 v69, v47
	v_mul_f32_e32 v73, v2, v2
	v_mul_f32_e32 v74, v3, v3
	v_mov_b32_e32 v59, v57
	v_mov_b32_e32 v61, v71
	v_pk_add_f32 v[62:63], v[62:63], v[64:65]
	v_pk_add_f32 v[48:49], v[48:49], v[68:69]
	v_pk_add_f32 v[44:45], v[44:45], v[44:45] op_sel:[0,1] op_sel_hi:[1,0]
	v_pk_add_f32 v[42:43], v[42:43], v[42:43] op_sel:[0,1] op_sel_hi:[1,0]
	s_waitcnt vmcnt(1)
	v_mul_f32_e32 v77, v6, v6
	v_mul_f32_e32 v78, v7, v7
	v_pk_add_f32 v[58:59], v[58:59], v[60:61]
	v_mov_b32_e32 v45, v73
	v_mov_b32_e32 v43, v74
	v_pk_add_f32 v[60:61], v[62:63], v[62:63] op_sel:[0,1] op_sel_hi:[1,0]
	v_pk_add_f32 v[48:49], v[48:49], v[48:49] op_sel:[0,1] op_sel_hi:[1,0]
	v_pk_add_f32 v[42:43], v[44:45], v[42:43]
	v_mov_b32_e32 v61, v77
	v_mov_b32_e32 v49, v78
	v_pk_add_f32 v[42:43], v[42:43], v[58:59]
	v_pk_add_f32 v[44:45], v[60:61], v[48:49]
	s_waitcnt vmcnt(0)
	v_mul_f32_e32 v70, v11, v11
	v_mul_f32_e32 v72, v13, v13
	v_mul_f32_e32 v75, v8, v8
	v_mul_f32_e32 v76, v9, v9
	v_pk_fma_f32 v[46:47], v[10:11], v[10:11], v[70:71] op_sel_hi:[1,1,0]
	v_pk_fma_f32 v[66:67], v[12:13], v[12:13], v[72:73] op_sel_hi:[1,1,0]
	v_mov_b32_e32 v47, v75
	v_mov_b32_e32 v67, v76
	v_pk_add_f32 v[46:47], v[46:47], v[66:67]
	v_add_f32_e32 v48, v42, v43
	v_pk_add_f32 v[42:43], v[44:45], v[46:47]
	ds_bpermute_b32 v44, v35, v48
	v_add_f32_e32 v42, v42, v43
	ds_bpermute_b32 v43, v35, v42
	s_waitcnt lgkmcnt(1)
	v_add_f32_e32 v44, v48, v44
	ds_bpermute_b32 v45, v50, v44
	s_waitcnt lgkmcnt(1)
	v_add_f32_e32 v42, v42, v43
	ds_bpermute_b32 v43, v50, v42
	s_waitcnt lgkmcnt(1)
	v_add_f32_e32 v44, v44, v45
	ds_bpermute_b32 v45, v51, v44
	s_waitcnt lgkmcnt(1)
	v_add_f32_e32 v42, v42, v43
	ds_bpermute_b32 v43, v51, v42
	s_waitcnt lgkmcnt(1)
	v_add_f32_e32 v44, v44, v45
	ds_bpermute_b32 v45, v52, v44
	s_waitcnt lgkmcnt(1)
	v_add_f32_e32 v42, v42, v43
	ds_bpermute_b32 v43, v52, v42
	s_waitcnt lgkmcnt(1)
	v_add_f32_e32 v44, v44, v45
	ds_bpermute_b32 v45, v53, v44
	s_waitcnt lgkmcnt(1)
	v_add_f32_e32 v42, v42, v43
	ds_bpermute_b32 v43, v53, v42
	s_waitcnt lgkmcnt(1)
	v_add_f32_e32 v44, v44, v45
	ds_bpermute_b32 v45, v54, v44
	s_waitcnt lgkmcnt(1)
	v_add_f32_e32 v42, v42, v43
	ds_bpermute_b32 v43, v54, v42
	s_waitcnt lgkmcnt(1)
	v_add_f32_e32 v44, v44, v45
	v_fmamk_f32 v44, v44, 0x3a800000, v55
	s_waitcnt lgkmcnt(0)
	v_add_f32_e32 v42, v42, v43
	v_mul_f32_e32 v43, 0x4f800000, v44
	v_cmp_gt_f32_e32 vcc, s13, v44
	v_fmamk_f32 v42, v42, 0x3a800000, v55
	v_cmp_gt_f32_e64 s[6:7], s13, v42
	v_cndmask_b32_e32 v43, v44, v43, vcc
	v_mul_f32_e32 v44, 0x4f800000, v42
	v_sqrt_f32_e32 v45, v43
	v_cndmask_b32_e64 v42, v42, v44, s[6:7]
	v_sqrt_f32_e32 v44, v42
	v_add_u32_e32 v46, -1, v45
	v_add_u32_e32 v47, 1, v45
	v_fma_f32 v48, -v46, v45, v43
	v_fma_f32 v49, -v47, v45, v43
	v_add_u32_e32 v57, -1, v44
	v_cmp_ge_f32_e64 s[8:9], 0, v48
	v_add_u32_e32 v62, 1, v44
	v_fma_f32 v48, -v62, v44, v42
	v_cndmask_b32_e64 v45, v45, v46, s[8:9]
	v_fma_f32 v46, -v57, v44, v42
	v_cmp_lt_f32_e64 s[8:9], 0, v49
	s_nop 1
	v_cndmask_b32_e64 v45, v45, v47, s[8:9]
	v_cmp_ge_f32_e64 s[8:9], 0, v46
	v_mul_f32_e32 v46, 0x37800000, v45
	v_cndmask_b32_e32 v45, v45, v46, vcc
	v_cndmask_b32_e64 v44, v44, v57, s[8:9]
	v_cmp_lt_f32_e64 s[8:9], 0, v48
	v_cmp_class_f32_e32 vcc, v43, v56
	s_nop 0
	v_cndmask_b32_e64 v44, v44, v62, s[8:9]
	v_mul_f32_e32 v46, 0x37800000, v44
	v_cndmask_b32_e32 v43, v45, v43, vcc
	v_cndmask_b32_e64 v44, v44, v46, s[6:7]
	v_div_scale_f32 v45, s[6:7], v43, v43, 1.0
	v_cmp_class_f32_e64 s[6:7], v42, v56
	v_div_scale_f32 v46, vcc, 1.0, v43, 1.0
	s_nop 0
	v_cndmask_b32_e64 v42, v44, v42, s[6:7]
	v_rcp_f32_e32 v44, v45
	v_div_scale_f32 v47, s[6:7], v42, v42, 1.0
	v_rcp_f32_e32 v49, v47
	v_fma_f32 v48, -v45, v44, 1.0
	v_fmac_f32_e32 v44, v48, v44
	v_mul_f32_e32 v62, v46, v44
	v_fma_f32 v48, -v47, v49, 1.0
	v_fmac_f32_e32 v49, v48, v49
	v_fma_f32 v48, -v45, v62, v46
	v_fmac_f32_e32 v62, v48, v44
	v_fma_f32 v45, -v45, v62, v46
	v_div_scale_f32 v57, s[6:7], 1.0, v42, 1.0
	v_div_fmas_f32 v44, v45, v44, v62
	v_div_fixup_f32 v48, v44, v43, 1.0
	v_mul_f32_e32 v43, v57, v49
	v_fma_f32 v44, -v47, v43, v57
	v_fmac_f32_e32 v43, v44, v49
	v_fma_f32 v44, -v47, v43, v57
	s_mov_b64 vcc, s[6:7]
	v_div_fmas_f32 v43, v44, v49, v43
	v_div_fixup_f32 v46, v43, v42, 1.0
	v_pk_mul_f32 v[26:27], v[26:27], v[48:49] op_sel_hi:[1,0]
	v_lshl_add_u64 v[44:45], v[40:41], 0, s[30:31]
	v_lshl_add_u64 v[42:43], v[40:41], 0, s[34:35]
	v_pk_mul_f32 v[28:29], v[28:29], v[48:49] op_sel_hi:[1,0]
	v_pk_mul_f32 v[26:27], v[208:209], v[26:27]
	v_pk_mul_f32 v[30:31], v[30:31], v[46:47] op_sel_hi:[1,0]
	v_pk_mul_f32 v[32:33], v[32:33], v[46:47] op_sel_hi:[1,0]
	v_pk_mul_f32 v[28:29], v[210:211], v[28:29]
	v_pk_mul_f32 v[32:33], v[210:211], v[32:33]
	v_pk_mul_f32 v[30:31], v[208:209], v[30:31]
	v_cvt_pk_bf16_f32 v58, v26, v27
	v_cvt_pk_bf16_f32 v59, v28, v29
	s_nop 0
	v_cvt_pk_bf16_f32 v26, v30, v31
	v_cvt_pk_bf16_f32 v27, v32, v33
	global_store_dwordx2 v[44:45], v[58:59], off
	s_cbranch_scc1 .LBB0_1325
	global_store_dwordx2 v[42:43], v[26:27], off
; __device__ __forceinline__ unsigned cvt_pk_bf16(float lo, float hi) { unsigned r; asm volatile("v_cvt_pk_bf16_f32 %0, %1, %2" : "=v"(r) : "v"(lo), "v"(hi)); return r; }
; __device__ __forceinline__ void rms_pass(const float* X, const float* g, bf16_t* O, float* F, int rows, int gw, int NGW) {
;     ...
;         for (int j = 0; j < 4; ++j) {
;             const f32x4 gg = gr[64 * j]; const f32x4 y0 = v0[j] * r0 * gg, y1 = v1[j] * r1 * gg;
;             u32x2 w0, w1; w0.x = cvt_pk_bf16(y0.x, y0.y); w0.y = cvt_pk_bf16(y0.z, y0.w); w1.x = cvt_pk_bf16(y1.x, y1.y); w1.y = cvt_pk_bf16(y1.z, y1.w);
;             *((u32x2*)(O + (size_t)m * 1024) + lane + 64 * j) = w0;
;             if (two) *((u32x2*)(O + (size_t)m1 * 1024) + lane + 64 * j) = w1;
;         }
.LBB0_1325:
	v_mov_b32_e32 v49, v48
	v_mov_b32_e32 v47, v46
	v_mov_b32_e32 v28, v48
	v_mov_b32_e32 v29, v48
	v_mov_b32_e32 v26, v46
	v_mov_b32_e32 v27, v46
	v_cndmask_b32_e64 v57, 0, 1, s[14:15]
	v_pk_mul_f32 v[18:19], v[18:19], v[48:49]
	v_pk_mul_f32 v[20:21], v[20:21], v[28:29]
	v_pk_mul_f32 v[24:25], v[24:25], v[26:27]
	v_pk_mul_f32 v[22:23], v[22:23], v[46:47]
	v_cmp_ne_u32_e64 s[6:7], 1, v57
	s_andn2_b64 vcc, exec, s[14:15]
	v_pk_mul_f32 v[18:19], v[18:19], v[212:213]
	v_pk_mul_f32 v[20:21], v[20:21], v[214:215]
	v_pk_mul_f32 v[24:25], v[24:25], v[214:215]
	v_pk_mul_f32 v[22:23], v[22:23], v[212:213]
	v_cvt_pk_bf16_f32 v30, v18, v19
	v_cvt_pk_bf16_f32 v31, v20, v21
	s_nop 0
	v_cvt_pk_bf16_f32 v18, v22, v23
	v_cvt_pk_bf16_f32 v19, v24, v25
	global_store_dwordx2 v[44:45], v[30:31], off offset:512
	s_cbranch_vccnz .LBB0_1327
	global_store_dwordx2 v[42:43], v[18:19], off offset:512
.LBB0_1327:
	v_pk_mul_f32 v[14:15], v[14:15], v[48:49]
	v_pk_mul_f32 v[10:11], v[10:11], v[46:47]
	v_pk_mul_f32 v[16:17], v[16:17], v[28:29]
	v_pk_mul_f32 v[12:13], v[12:13], v[26:27]
	s_and_b64 vcc, exec, s[6:7]
	v_pk_mul_f32 v[14:15], v[14:15], v[216:217]
	v_pk_mul_f32 v[10:11], v[10:11], v[216:217]
	v_pk_mul_f32 v[16:17], v[16:17], v[218:219]
	v_pk_mul_f32 v[12:13], v[12:13], v[218:219]
	v_cvt_pk_bf16_f32 v14, v14, v15
	v_cvt_pk_bf16_f32 v15, v16, v17
	v_cvt_pk_bf16_f32 v10, v10, v11
	s_nop 0
	v_cvt_pk_bf16_f32 v11, v12, v13
	global_store_dwordx2 v[44:45], v[14:15], off offset:1024
	s_cbranch_vccnz .LBB0_1329
	global_store_dwordx2 v[42:43], v[10:11], off offset:1024
.LBB0_1329:
	v_mov_b32_e32 v14, v48
	v_mov_b32_e32 v15, v48
	v_pk_mul_f32 v[2:3], v[2:3], v[48:49]
	v_mov_b32_e32 v16, v46
	v_mov_b32_e32 v17, v46
	v_pk_mul_f32 v[6:7], v[6:7], v[46:47]
	v_pk_mul_f32 v[4:5], v[4:5], v[14:15]
	v_pk_mul_f32 v[8:9], v[8:9], v[16:17]
	s_and_b64 vcc, exec, s[6:7]
	v_pk_mul_f32 v[2:3], v[2:3], v[220:221]
	v_pk_mul_f32 v[4:5], v[4:5], v[222:223]
	v_pk_mul_f32 v[8:9], v[8:9], v[222:223]
	v_pk_mul_f32 v[6:7], v[6:7], v[220:221]
	v_cvt_pk_bf16_f32 v10, v2, v3
	v_cvt_pk_bf16_f32 v11, v4, v5
	s_nop 0
	v_cvt_pk_bf16_f32 v2, v6, v7
	v_cvt_pk_bf16_f32 v3, v8, v9
	global_store_dwordx2 v[44:45], v[10:11], off offset:1536
	s_cbranch_vccnz .LBB0_1322
	global_store_dwordx2 v[42:43], v[2:3], off offset:1536
	s_branch .LBB0_1322
